# LDS-DMA loops: fragment reads reordered (A0,B0,B1,...) with per-MFMA counted lgkmcnt waits
# baseline (speedup 1.0000x reference)
.Lf2_stage0:
	ds_read_b128 v[66:69], v130 offset:0
	ds_read_b128 v[74:77], v134 offset:16384
	ds_read_b128 v[78:81], v134 offset:20480
	ds_read_b128 v[70:73], v130 offset:4096
	s_cmp_ge_u32 s22, 43
	s_cbranch_scc1 .Lf2_nl0
	s_add_u32 m0, s38, 0x8000
	ds_read_b128 v[82:85], v131 offset:0
	global_load_lds_dwordx4 v152, s[10:11]
	s_add_u32 m0, s38, 0xc000
	ds_read_b128 v[90:93], v135 offset:16384
	global_load_lds_dwordx4 v152, s[8:9]
	s_add_u32 m0, s38, 0x9000
	ds_read_b128 v[94:97], v135 offset:20480
	global_load_lds_dwordx4 v150, s[10:11]
	s_add_u32 m0, s38, 0xd000
	ds_read_b128 v[86:89], v131 offset:4096
	global_load_lds_dwordx4 v150, s[8:9]
	s_add_u32 m0, s38, 0xa000
	ds_read_b128 v[98:101], v132 offset:0
	global_load_lds_dwordx4 v148, s[10:11]
	s_add_u32 m0, s38, 0xe000
	ds_read_b128 v[106:109], v136 offset:16384
	global_load_lds_dwordx4 v148, s[8:9]
	s_add_u32 m0, s38, 0xb000
	ds_read_b128 v[110:113], v136 offset:20480
	global_load_lds_dwordx4 v146, s[10:11]
	s_add_u32 m0, s38, 0xf000
	ds_read_b128 v[102:105], v132 offset:4096
	global_load_lds_dwordx4 v146, s[8:9]
	s_add_u32 s8, s8, 0x80
	s_addc_u32 s9, s9, 0
	s_add_u32 s10, s10, 0x80
	s_addc_u32 s11, s11, 0
	s_branch .Lf2_dd0
.Lf2_nl0:
	ds_read_b128 v[82:85], v131 offset:0
	ds_read_b128 v[90:93], v135 offset:16384
	ds_read_b128 v[94:97], v135 offset:20480
	ds_read_b128 v[86:89], v131 offset:4096
	ds_read_b128 v[98:101], v132 offset:0
	ds_read_b128 v[106:109], v136 offset:16384
	ds_read_b128 v[110:113], v136 offset:20480
	ds_read_b128 v[102:105], v132 offset:4096
.Lf2_dd0:
	s_waitcnt lgkmcnt(10)
	v_mfma_f32_32x32x16_f16 v[50:65], v[66:69], v[74:77], v[50:65]
	s_waitcnt lgkmcnt(9)
	v_mfma_f32_32x32x16_f16 v[34:49], v[66:69], v[78:81], v[34:49]
	s_waitcnt lgkmcnt(8)
	v_mfma_f32_32x32x16_f16 v[18:33], v[70:73], v[74:77], v[18:33]
	v_mfma_f32_32x32x16_f16 v[2:17], v[70:73], v[78:81], v[2:17]
	ds_read_b128 v[114:117], v133 offset:0
	ds_read_b128 v[122:125], v137 offset:16384
	ds_read_b128 v[126:129], v137 offset:20480
	ds_read_b128 v[118:121], v133 offset:4096
	s_waitcnt lgkmcnt(10)
	v_mfma_f32_32x32x16_f16 v[50:65], v[82:85], v[90:93], v[50:65]
	s_waitcnt lgkmcnt(9)
	v_mfma_f32_32x32x16_f16 v[34:49], v[82:85], v[94:97], v[34:49]
	s_waitcnt lgkmcnt(8)
	v_mfma_f32_32x32x16_f16 v[18:33], v[86:89], v[90:93], v[18:33]
	v_mfma_f32_32x32x16_f16 v[2:17], v[86:89], v[94:97], v[2:17]
	s_waitcnt lgkmcnt(6)
	v_mfma_f32_32x32x16_f16 v[50:65], v[98:101], v[106:109], v[50:65]
	s_waitcnt lgkmcnt(5)
	v_mfma_f32_32x32x16_f16 v[34:49], v[98:101], v[110:113], v[34:49]
	s_waitcnt lgkmcnt(4)
	v_mfma_f32_32x32x16_f16 v[18:33], v[102:105], v[106:109], v[18:33]
	v_mfma_f32_32x32x16_f16 v[2:17], v[102:105], v[110:113], v[2:17]
	s_waitcnt lgkmcnt(2)
	v_mfma_f32_32x32x16_f16 v[50:65], v[114:117], v[122:125], v[50:65]
	s_waitcnt lgkmcnt(1)
	v_mfma_f32_32x32x16_f16 v[34:49], v[114:117], v[126:129], v[34:49]
	s_waitcnt lgkmcnt(0)
	v_mfma_f32_32x32x16_f16 v[18:33], v[118:121], v[122:125], v[18:33]
	v_mfma_f32_32x32x16_f16 v[2:17], v[118:121], v[126:129], v[2:17]
	s_add_i32 s22, s22, 1
	s_waitcnt vmcnt(0)
	s_barrier
.Lf2_stage1:
	ds_read_b128 v[66:69], v130 offset:32768
	ds_read_b128 v[74:77], v134 offset:49152
	ds_read_b128 v[78:81], v134 offset:53248
	ds_read_b128 v[70:73], v130 offset:36864
	s_cmp_ge_u32 s22, 43
	s_cbranch_scc1 .Lf2_nl1
	s_add_u32 m0, s38, 0x0
	ds_read_b128 v[82:85], v131 offset:32768
	global_load_lds_dwordx4 v152, s[10:11]
	s_add_u32 m0, s38, 0x4000
	ds_read_b128 v[90:93], v135 offset:49152
	global_load_lds_dwordx4 v152, s[8:9]
	s_add_u32 m0, s38, 0x1000
	ds_read_b128 v[94:97], v135 offset:53248
	global_load_lds_dwordx4 v150, s[10:11]
	s_add_u32 m0, s38, 0x5000
	ds_read_b128 v[86:89], v131 offset:36864
	global_load_lds_dwordx4 v150, s[8:9]
	s_add_u32 m0, s38, 0x2000
	ds_read_b128 v[98:101], v132 offset:32768
	global_load_lds_dwordx4 v148, s[10:11]
	s_add_u32 m0, s38, 0x6000
	ds_read_b128 v[106:109], v136 offset:49152
	global_load_lds_dwordx4 v148, s[8:9]
	s_add_u32 m0, s38, 0x3000
	ds_read_b128 v[110:113], v136 offset:53248
	global_load_lds_dwordx4 v146, s[10:11]
	s_add_u32 m0, s38, 0x7000
	ds_read_b128 v[102:105], v132 offset:36864
	global_load_lds_dwordx4 v146, s[8:9]
	s_add_u32 s8, s8, 0x80
	s_addc_u32 s9, s9, 0
	s_add_u32 s10, s10, 0x80
	s_addc_u32 s11, s11, 0
	s_branch .Lf2_dd1
.Lf2_nl1:
	ds_read_b128 v[82:85], v131 offset:32768
	ds_read_b128 v[90:93], v135 offset:49152
	ds_read_b128 v[94:97], v135 offset:53248
	ds_read_b128 v[86:89], v131 offset:36864
	ds_read_b128 v[98:101], v132 offset:32768
	ds_read_b128 v[106:109], v136 offset:49152
	ds_read_b128 v[110:113], v136 offset:53248
	ds_read_b128 v[102:105], v132 offset:36864
.Lf2_dd1:
	s_waitcnt lgkmcnt(10)
	v_mfma_f32_32x32x16_f16 v[50:65], v[66:69], v[74:77], v[50:65]
	s_waitcnt lgkmcnt(9)
	v_mfma_f32_32x32x16_f16 v[34:49], v[66:69], v[78:81], v[34:49]
	s_waitcnt lgkmcnt(8)
	v_mfma_f32_32x32x16_f16 v[18:33], v[70:73], v[74:77], v[18:33]
	v_mfma_f32_32x32x16_f16 v[2:17], v[70:73], v[78:81], v[2:17]
	ds_read_b128 v[114:117], v133 offset:32768
	ds_read_b128 v[122:125], v137 offset:49152
	ds_read_b128 v[126:129], v137 offset:53248
	ds_read_b128 v[118:121], v133 offset:36864
	s_waitcnt lgkmcnt(10)
	v_mfma_f32_32x32x16_f16 v[50:65], v[82:85], v[90:93], v[50:65]
	s_waitcnt lgkmcnt(9)
	v_mfma_f32_32x32x16_f16 v[34:49], v[82:85], v[94:97], v[34:49]
	s_waitcnt lgkmcnt(8)
	v_mfma_f32_32x32x16_f16 v[18:33], v[86:89], v[90:93], v[18:33]
	v_mfma_f32_32x32x16_f16 v[2:17], v[86:89], v[94:97], v[2:17]
	s_waitcnt lgkmcnt(6)
	v_mfma_f32_32x32x16_f16 v[50:65], v[98:101], v[106:109], v[50:65]
	s_waitcnt lgkmcnt(5)
	v_mfma_f32_32x32x16_f16 v[34:49], v[98:101], v[110:113], v[34:49]
	s_waitcnt lgkmcnt(4)
	v_mfma_f32_32x32x16_f16 v[18:33], v[102:105], v[106:109], v[18:33]
	v_mfma_f32_32x32x16_f16 v[2:17], v[102:105], v[110:113], v[2:17]
	s_waitcnt lgkmcnt(2)
	v_mfma_f32_32x32x16_f16 v[50:65], v[114:117], v[122:125], v[50:65]
	s_waitcnt lgkmcnt(1)
	v_mfma_f32_32x32x16_f16 v[34:49], v[114:117], v[126:129], v[34:49]
	s_waitcnt lgkmcnt(0)
	v_mfma_f32_32x32x16_f16 v[18:33], v[118:121], v[122:125], v[18:33]
	v_mfma_f32_32x32x16_f16 v[2:17], v[118:121], v[126:129], v[2:17]
	s_add_i32 s22, s22, 1
	s_cmp_ge_u32 s22, 44
	s_cbranch_scc1 .LBB0_57
	s_waitcnt vmcnt(0)
	s_barrier
	s_branch .Lf2_stage0

.Lfg_stage0:
	ds_read_b128 v[178:181], v130 offset:0
	ds_read_b128 v[194:197], v132 offset:16384
	ds_read_b128 v[198:201], v132 offset:18432
	ds_read_b128 v[182:185], v130 offset:2048
	ds_read_b128 v[186:189], v130 offset:4096
	ds_read_b128 v[190:193], v130 offset:6144
	s_cmp_ge_u32 s13, 31
	s_cbranch_scc1 .Lfg_nl0
	s_add_u32 m0, s18, 0x6000
	ds_read_b128 v[216:219], v131 offset:0
	global_load_lds_dwordx4 v139, s[14:15]
	s_add_u32 m0, s18, 0x7000
	ds_read_b128 v[234:237], v133 offset:16384
	global_load_lds_dwordx4 v140, s[14:15]
	s_add_u32 m0, s18, 0x8000
	ds_read_b128 v[240:243], v133 offset:18432
	global_load_lds_dwordx4 v141, s[14:15]
	s_add_u32 m0, s18, 0x9000
	ds_read_b128 v[220:223], v131 offset:2048
	global_load_lds_dwordx4 v142, s[14:15]
	s_add_u32 m0, s18, 0xa000
	ds_read_b128 v[226:229], v131 offset:4096
	global_load_lds_dwordx4 v143, s[16:17]
	s_add_u32 m0, s18, 0xb000
	ds_read_b128 v[230:233], v131 offset:6144
	global_load_lds_dwordx4 v144, s[16:17]
	s_add_u32 s14, s14, 64
	s_addc_u32 s15, s15, 0
	s_add_u32 s16, s16, 64
	s_addc_u32 s17, s17, 0
	s_branch .Lfg_dd0
.Lfg_nl0:
	ds_read_b128 v[216:219], v131 offset:0
	ds_read_b128 v[234:237], v133 offset:16384
	ds_read_b128 v[240:243], v133 offset:18432
	ds_read_b128 v[220:223], v131 offset:2048
	ds_read_b128 v[226:229], v131 offset:4096
	ds_read_b128 v[230:233], v131 offset:6144
.Lfg_dd0:
	s_waitcnt lgkmcnt(10)
	v_mfma_f32_32x32x16_f16 v[114:129], v[178:181], v[194:197], v[114:129]
	s_waitcnt lgkmcnt(9)
	v_mfma_f32_32x32x16_f16 v[98:113], v[178:181], v[198:201], v[98:113]
	s_waitcnt lgkmcnt(8)
	v_mfma_f32_32x32x16_f16 v[82:97], v[182:185], v[194:197], v[82:97]
	v_mfma_f32_32x32x16_f16 v[66:81], v[182:185], v[198:201], v[66:81]
	s_waitcnt lgkmcnt(7)
	v_mfma_f32_32x32x16_f16 v[50:65], v[186:189], v[194:197], v[50:65]
	v_mfma_f32_32x32x16_f16 v[34:49], v[186:189], v[198:201], v[34:49]
	s_waitcnt lgkmcnt(6)
	v_mfma_f32_32x32x16_f16 v[18:33], v[190:193], v[194:197], v[18:33]
	v_mfma_f32_32x32x16_f16 v[2:17], v[190:193], v[198:201], v[2:17]
	s_waitcnt lgkmcnt(4)
	v_mfma_f32_32x32x16_f16 v[114:129], v[216:219], v[234:237], v[114:129]
	s_waitcnt lgkmcnt(3)
	v_mfma_f32_32x32x16_f16 v[98:113], v[216:219], v[240:243], v[98:113]
	s_waitcnt lgkmcnt(2)
	v_mfma_f32_32x32x16_f16 v[82:97], v[220:223], v[234:237], v[82:97]
	v_mfma_f32_32x32x16_f16 v[66:81], v[220:223], v[240:243], v[66:81]
	s_waitcnt lgkmcnt(1)
	v_mfma_f32_32x32x16_f16 v[50:65], v[226:229], v[234:237], v[50:65]
	v_mfma_f32_32x32x16_f16 v[34:49], v[226:229], v[240:243], v[34:49]
	s_waitcnt lgkmcnt(0)
	v_mfma_f32_32x32x16_f16 v[18:33], v[230:233], v[234:237], v[18:33]
	v_mfma_f32_32x32x16_f16 v[2:17], v[230:233], v[240:243], v[2:17]
	s_add_i32 s13, s13, 1
	s_waitcnt vmcnt(0)
	s_barrier
.Lfg_stage1:
	ds_read_b128 v[178:181], v130 offset:24576
	ds_read_b128 v[194:197], v132 offset:40960
	ds_read_b128 v[198:201], v132 offset:43008
	ds_read_b128 v[182:185], v130 offset:26624
	ds_read_b128 v[186:189], v130 offset:28672
	ds_read_b128 v[190:193], v130 offset:30720
	s_cmp_ge_u32 s13, 31
	s_cbranch_scc1 .Lfg_nl1
	s_add_u32 m0, s18, 0x0
	ds_read_b128 v[216:219], v131 offset:24576
	global_load_lds_dwordx4 v139, s[14:15]
	s_add_u32 m0, s18, 0x1000
	ds_read_b128 v[234:237], v133 offset:40960
	global_load_lds_dwordx4 v140, s[14:15]
	s_add_u32 m0, s18, 0x2000
	ds_read_b128 v[240:243], v133 offset:43008
	global_load_lds_dwordx4 v141, s[14:15]
	s_add_u32 m0, s18, 0x3000
	ds_read_b128 v[220:223], v131 offset:26624
	global_load_lds_dwordx4 v142, s[14:15]
	s_add_u32 m0, s18, 0x4000
	ds_read_b128 v[226:229], v131 offset:28672
	global_load_lds_dwordx4 v143, s[16:17]
	s_add_u32 m0, s18, 0x5000
	ds_read_b128 v[230:233], v131 offset:30720
	global_load_lds_dwordx4 v144, s[16:17]
	s_add_u32 s14, s14, 64
	s_addc_u32 s15, s15, 0
	s_add_u32 s16, s16, 64
	s_addc_u32 s17, s17, 0
	s_branch .Lfg_dd1
.Lfg_nl1:
	ds_read_b128 v[216:219], v131 offset:24576
	ds_read_b128 v[234:237], v133 offset:40960
	ds_read_b128 v[240:243], v133 offset:43008
	ds_read_b128 v[220:223], v131 offset:26624
	ds_read_b128 v[226:229], v131 offset:28672
	ds_read_b128 v[230:233], v131 offset:30720
.Lfg_dd1:
	s_waitcnt lgkmcnt(10)
	v_mfma_f32_32x32x16_f16 v[114:129], v[178:181], v[194:197], v[114:129]
	s_waitcnt lgkmcnt(9)
	v_mfma_f32_32x32x16_f16 v[98:113], v[178:181], v[198:201], v[98:113]
	s_waitcnt lgkmcnt(8)
	v_mfma_f32_32x32x16_f16 v[82:97], v[182:185], v[194:197], v[82:97]
	v_mfma_f32_32x32x16_f16 v[66:81], v[182:185], v[198:201], v[66:81]
	s_waitcnt lgkmcnt(7)
	v_mfma_f32_32x32x16_f16 v[50:65], v[186:189], v[194:197], v[50:65]
	v_mfma_f32_32x32x16_f16 v[34:49], v[186:189], v[198:201], v[34:49]
	s_waitcnt lgkmcnt(6)
	v_mfma_f32_32x32x16_f16 v[18:33], v[190:193], v[194:197], v[18:33]
	v_mfma_f32_32x32x16_f16 v[2:17], v[190:193], v[198:201], v[2:17]
	s_waitcnt lgkmcnt(4)
	v_mfma_f32_32x32x16_f16 v[114:129], v[216:219], v[234:237], v[114:129]
	s_waitcnt lgkmcnt(3)
	v_mfma_f32_32x32x16_f16 v[98:113], v[216:219], v[240:243], v[98:113]
	s_waitcnt lgkmcnt(2)
	v_mfma_f32_32x32x16_f16 v[82:97], v[220:223], v[234:237], v[82:97]
	v_mfma_f32_32x32x16_f16 v[66:81], v[220:223], v[240:243], v[66:81]
	s_waitcnt lgkmcnt(1)
	v_mfma_f32_32x32x16_f16 v[50:65], v[226:229], v[234:237], v[50:65]
	v_mfma_f32_32x32x16_f16 v[34:49], v[226:229], v[240:243], v[34:49]
	s_waitcnt lgkmcnt(0)
	v_mfma_f32_32x32x16_f16 v[18:33], v[230:233], v[234:237], v[18:33]
	v_mfma_f32_32x32x16_f16 v[2:17], v[230:233], v[240:243], v[2:17]
	s_add_i32 s13, s13, 1
	s_cmp_ge_u32 s13, 32
	s_cbranch_scc1 .LBB0_69
	s_waitcnt vmcnt(0)
	s_barrier
	s_branch .Lfg_stage0

.Lwo_stage0:
	ds_read_b128 v[66:69], v130 offset:0
	ds_read_b128 v[74:77], v134 offset:16384
	ds_read_b128 v[78:81], v134 offset:20480
	ds_read_b128 v[70:73], v130 offset:4096
	s_cmp_ge_u32 s22, 15
	s_cbranch_scc1 .Lwo_nl0
	s_add_u32 m0, s38, 0x8000
	ds_read_b128 v[82:85], v131 offset:0
	global_load_lds_dwordx4 v152, s[10:11]
	s_add_u32 m0, s38, 0xc000
	ds_read_b128 v[90:93], v135 offset:16384
	global_load_lds_dwordx4 v152, s[8:9]
	s_add_u32 m0, s38, 0x9000
	ds_read_b128 v[94:97], v135 offset:20480
	global_load_lds_dwordx4 v150, s[10:11]
	s_add_u32 m0, s38, 0xd000
	ds_read_b128 v[86:89], v131 offset:4096
	global_load_lds_dwordx4 v150, s[8:9]
	s_add_u32 m0, s38, 0xa000
	ds_read_b128 v[98:101], v132 offset:0
	global_load_lds_dwordx4 v148, s[10:11]
	s_add_u32 m0, s38, 0xe000
	ds_read_b128 v[106:109], v136 offset:16384
	global_load_lds_dwordx4 v148, s[8:9]
	s_add_u32 m0, s38, 0xb000
	ds_read_b128 v[110:113], v136 offset:20480
	global_load_lds_dwordx4 v146, s[10:11]
	s_add_u32 m0, s38, 0xf000
	ds_read_b128 v[102:105], v132 offset:4096
	global_load_lds_dwordx4 v146, s[8:9]
	s_add_u32 s8, s8, 0x80
	s_addc_u32 s9, s9, 0
	s_add_u32 s10, s10, 0x80
	s_addc_u32 s11, s11, 0
	s_branch .Lwo_dd0

.Lwo_stage1:
	ds_read_b128 v[66:69], v130 offset:32768
	ds_read_b128 v[74:77], v134 offset:49152
	ds_read_b128 v[78:81], v134 offset:53248
	ds_read_b128 v[70:73], v130 offset:36864
	s_cmp_ge_u32 s22, 15
	s_cbranch_scc1 .Lwo_nl1
	s_add_u32 m0, s38, 0x0
	ds_read_b128 v[82:85], v131 offset:32768
	global_load_lds_dwordx4 v152, s[10:11]
	s_add_u32 m0, s38, 0x4000
	ds_read_b128 v[90:93], v135 offset:49152
	global_load_lds_dwordx4 v152, s[8:9]
	s_add_u32 m0, s38, 0x1000
	ds_read_b128 v[94:97], v135 offset:53248
	global_load_lds_dwordx4 v150, s[10:11]
	s_add_u32 m0, s38, 0x5000
	ds_read_b128 v[86:89], v131 offset:36864
	global_load_lds_dwordx4 v150, s[8:9]
	s_add_u32 m0, s38, 0x2000
	ds_read_b128 v[98:101], v132 offset:32768
	global_load_lds_dwordx4 v148, s[10:11]
	s_add_u32 m0, s38, 0x6000
	ds_read_b128 v[106:109], v136 offset:49152
	global_load_lds_dwordx4 v148, s[8:9]
	s_add_u32 m0, s38, 0x3000
	ds_read_b128 v[110:113], v136 offset:53248
	global_load_lds_dwordx4 v146, s[10:11]
	s_add_u32 m0, s38, 0x7000
	ds_read_b128 v[102:105], v132 offset:36864
	global_load_lds_dwordx4 v146, s[8:9]
	s_add_u32 s8, s8, 0x80
	s_addc_u32 s9, s9, 0
	s_add_u32 s10, s10, 0x80
	s_addc_u32 s11, s11, 0
	s_branch .Lwo_dd1

; DI void gemm_tile_deep(const h16* __restrict__ A, int lda, const h16* __restrict__ B, int ldb, int K, f32x16 (&acc)[2][2], h16* sm) {
;     ...
;   for (int kt = 0; kt < nk; kt += 2) {
;     DEEP_HALF(ra0, rb0, 0, kt)
;     DEEP_HALF(ra1, rb1, 1, kt + 1)
;   }
.Lwo_dd1:
	s_waitcnt lgkmcnt(10)
	v_mfma_f32_32x32x16_f16 v[50:65], v[66:69], v[74:77], v[50:65]
	s_waitcnt lgkmcnt(9)
	v_mfma_f32_32x32x16_f16 v[34:49], v[66:69], v[78:81], v[34:49]
	s_waitcnt lgkmcnt(8)
	v_mfma_f32_32x32x16_f16 v[18:33], v[70:73], v[74:77], v[18:33]
	v_mfma_f32_32x32x16_f16 v[2:17], v[70:73], v[78:81], v[2:17]
	ds_read_b128 v[114:117], v133 offset:32768
	ds_read_b128 v[122:125], v137 offset:49152
	ds_read_b128 v[126:129], v137 offset:53248
	ds_read_b128 v[118:121], v133 offset:36864
	s_waitcnt lgkmcnt(10)
	v_mfma_f32_32x32x16_f16 v[50:65], v[82:85], v[90:93], v[50:65]
	s_waitcnt lgkmcnt(9)
	v_mfma_f32_32x32x16_f16 v[34:49], v[82:85], v[94:97], v[34:49]
	s_waitcnt lgkmcnt(8)
	v_mfma_f32_32x32x16_f16 v[18:33], v[86:89], v[90:93], v[18:33]
	v_mfma_f32_32x32x16_f16 v[2:17], v[86:89], v[94:97], v[2:17]
	s_waitcnt lgkmcnt(6)
	v_mfma_f32_32x32x16_f16 v[50:65], v[98:101], v[106:109], v[50:65]
	s_waitcnt lgkmcnt(5)
	v_mfma_f32_32x32x16_f16 v[34:49], v[98:101], v[110:113], v[34:49]
	s_waitcnt lgkmcnt(4)
	v_mfma_f32_32x32x16_f16 v[18:33], v[102:105], v[106:109], v[18:33]
	v_mfma_f32_32x32x16_f16 v[2:17], v[102:105], v[110:113], v[2:17]
	s_waitcnt lgkmcnt(2)
	v_mfma_f32_32x32x16_f16 v[50:65], v[114:117], v[122:125], v[50:65]
	s_waitcnt lgkmcnt(1)
	v_mfma_f32_32x32x16_f16 v[34:49], v[114:117], v[126:129], v[34:49]
	s_waitcnt lgkmcnt(0)
	v_mfma_f32_32x32x16_f16 v[18:33], v[118:121], v[122:125], v[18:33]
	v_mfma_f32_32x32x16_f16 v[2:17], v[118:121], v[126:129], v[2:17]
	s_add_i32 s22, s22, 1
	s_cmp_ge_u32 s22, 16
	s_cbranch_scc1 .LBB0_90
	s_waitcnt vmcnt(0)
	s_barrier
	s_branch .Lwo_stage0

.Lpg_stage0:
	ds_read_b128 v[178:181], v130 offset:0
	ds_read_b128 v[194:197], v132 offset:16384
	ds_read_b128 v[198:201], v132 offset:18432
	ds_read_b128 v[182:185], v130 offset:2048
	ds_read_b128 v[186:189], v130 offset:4096
	ds_read_b128 v[190:193], v130 offset:6144
	s_cmp_ge_u32 s1, 31
	s_cbranch_scc1 .Lpg_nl0
	s_add_u32 m0, s18, 0x6000
	ds_read_b128 v[216:219], v131 offset:0
	global_load_lds_dwordx4 v139, s[4:5]
	s_add_u32 m0, s18, 0x7000
	ds_read_b128 v[234:237], v133 offset:16384
	global_load_lds_dwordx4 v140, s[4:5]
	s_add_u32 m0, s18, 0x8000
	ds_read_b128 v[240:243], v133 offset:18432
	global_load_lds_dwordx4 v141, s[4:5]
	s_add_u32 m0, s18, 0x9000
	ds_read_b128 v[220:223], v131 offset:2048
	global_load_lds_dwordx4 v142, s[4:5]
	s_add_u32 m0, s18, 0xa000
	ds_read_b128 v[226:229], v131 offset:4096
	global_load_lds_dwordx4 v143, s[6:7]
	s_add_u32 m0, s18, 0xb000
	ds_read_b128 v[230:233], v131 offset:6144
	global_load_lds_dwordx4 v144, s[6:7]
	s_add_u32 s4, s4, 64
	s_addc_u32 s5, s5, 0
	s_add_u32 s6, s6, 64
	s_addc_u32 s7, s7, 0
	s_branch .Lpg_dd0

.Lpg_dd0:
	s_waitcnt lgkmcnt(10)
	v_mfma_f32_32x32x16_f16 v[114:129], v[178:181], v[194:197], v[114:129]
	s_waitcnt lgkmcnt(9)
	v_mfma_f32_32x32x16_f16 v[98:113], v[178:181], v[198:201], v[98:113]
	s_waitcnt lgkmcnt(8)
	v_mfma_f32_32x32x16_f16 v[82:97], v[182:185], v[194:197], v[82:97]
	v_mfma_f32_32x32x16_f16 v[66:81], v[182:185], v[198:201], v[66:81]
	s_waitcnt lgkmcnt(7)
	v_mfma_f32_32x32x16_f16 v[50:65], v[186:189], v[194:197], v[50:65]
	v_mfma_f32_32x32x16_f16 v[34:49], v[186:189], v[198:201], v[34:49]
	s_waitcnt lgkmcnt(6)
	v_mfma_f32_32x32x16_f16 v[18:33], v[190:193], v[194:197], v[18:33]
	v_mfma_f32_32x32x16_f16 v[2:17], v[190:193], v[198:201], v[2:17]
	s_waitcnt lgkmcnt(4)
	v_mfma_f32_32x32x16_f16 v[114:129], v[216:219], v[234:237], v[114:129]
	s_waitcnt lgkmcnt(3)
	v_mfma_f32_32x32x16_f16 v[98:113], v[216:219], v[240:243], v[98:113]
	s_waitcnt lgkmcnt(2)
	v_mfma_f32_32x32x16_f16 v[82:97], v[220:223], v[234:237], v[82:97]
	v_mfma_f32_32x32x16_f16 v[66:81], v[220:223], v[240:243], v[66:81]
	s_waitcnt lgkmcnt(1)
	v_mfma_f32_32x32x16_f16 v[50:65], v[226:229], v[234:237], v[50:65]
	v_mfma_f32_32x32x16_f16 v[34:49], v[226:229], v[240:243], v[34:49]
	s_waitcnt lgkmcnt(0)
	v_mfma_f32_32x32x16_f16 v[18:33], v[230:233], v[234:237], v[18:33]
	v_mfma_f32_32x32x16_f16 v[2:17], v[230:233], v[240:243], v[2:17]
	s_add_i32 s1, s1, 1
	s_waitcnt vmcnt(0)
	s_barrier
.Lpg_stage1:
	ds_read_b128 v[178:181], v130 offset:24576
	ds_read_b128 v[194:197], v132 offset:40960
	ds_read_b128 v[198:201], v132 offset:43008
	ds_read_b128 v[182:185], v130 offset:26624
	ds_read_b128 v[186:189], v130 offset:28672
	ds_read_b128 v[190:193], v130 offset:30720
	s_cmp_ge_u32 s1, 31
	s_cbranch_scc1 .Lpg_nl1
	s_add_u32 m0, s18, 0x0
	ds_read_b128 v[216:219], v131 offset:24576
	global_load_lds_dwordx4 v139, s[4:5]
	s_add_u32 m0, s18, 0x1000
	ds_read_b128 v[234:237], v133 offset:40960
	global_load_lds_dwordx4 v140, s[4:5]
	s_add_u32 m0, s18, 0x2000
	ds_read_b128 v[240:243], v133 offset:43008
	global_load_lds_dwordx4 v141, s[4:5]
	s_add_u32 m0, s18, 0x3000
	ds_read_b128 v[220:223], v131 offset:26624
	global_load_lds_dwordx4 v142, s[4:5]
	s_add_u32 m0, s18, 0x4000
	ds_read_b128 v[226:229], v131 offset:28672
	global_load_lds_dwordx4 v143, s[6:7]
	s_add_u32 m0, s18, 0x5000
	ds_read_b128 v[230:233], v131 offset:30720
	global_load_lds_dwordx4 v144, s[6:7]
	s_add_u32 s4, s4, 64
	s_addc_u32 s5, s5, 0
	s_add_u32 s6, s6, 64
	s_addc_u32 s7, s7, 0
	s_branch .Lpg_dd1

.Lpg_dd1:
	s_waitcnt lgkmcnt(10)
	v_mfma_f32_32x32x16_f16 v[114:129], v[178:181], v[194:197], v[114:129]
	s_waitcnt lgkmcnt(9)
	v_mfma_f32_32x32x16_f16 v[98:113], v[178:181], v[198:201], v[98:113]
	s_waitcnt lgkmcnt(8)
	v_mfma_f32_32x32x16_f16 v[82:97], v[182:185], v[194:197], v[82:97]
	v_mfma_f32_32x32x16_f16 v[66:81], v[182:185], v[198:201], v[66:81]
	s_waitcnt lgkmcnt(7)
	v_mfma_f32_32x32x16_f16 v[50:65], v[186:189], v[194:197], v[50:65]
	v_mfma_f32_32x32x16_f16 v[34:49], v[186:189], v[198:201], v[34:49]
	s_waitcnt lgkmcnt(6)
	v_mfma_f32_32x32x16_f16 v[18:33], v[190:193], v[194:197], v[18:33]
	v_mfma_f32_32x32x16_f16 v[2:17], v[190:193], v[198:201], v[2:17]
	s_waitcnt lgkmcnt(4)
	v_mfma_f32_32x32x16_f16 v[114:129], v[216:219], v[234:237], v[114:129]
	s_waitcnt lgkmcnt(3)
	v_mfma_f32_32x32x16_f16 v[98:113], v[216:219], v[240:243], v[98:113]
	s_waitcnt lgkmcnt(2)
	v_mfma_f32_32x32x16_f16 v[82:97], v[220:223], v[234:237], v[82:97]
	v_mfma_f32_32x32x16_f16 v[66:81], v[220:223], v[240:243], v[66:81]
	s_waitcnt lgkmcnt(1)
	v_mfma_f32_32x32x16_f16 v[50:65], v[226:229], v[234:237], v[50:65]
	v_mfma_f32_32x32x16_f16 v[34:49], v[226:229], v[240:243], v[34:49]
	s_waitcnt lgkmcnt(0)
	v_mfma_f32_32x32x16_f16 v[18:33], v[230:233], v[234:237], v[18:33]
	v_mfma_f32_32x32x16_f16 v[2:17], v[230:233], v[240:243], v[2:17]
	s_add_i32 s1, s1, 1
	s_cmp_ge_u32 s1, 32
	s_cbranch_scc1 .LBB0_700
	s_waitcnt vmcnt(0)
	s_barrier
	s_branch .Lpg_stage0
